# stack8: adds P3 glr tail with all loads up front and P10 q-epilogue gain loads pipelined
# speedup vs baseline: 1.0038x; 1.0035x over previous
; #define LAS __attribute__((address_space(3)))
; __device__ __forceinline__ unsigned pk2(float lo, float hi) { return pg8::cvt_pk_bf16(lo, hi); }
; __device__ __forceinline__ float row_rs(const float* ssq, int row, int fq) {
;     const f32x4 a = *(const f32x4*)(ssq + (size_t)row * 32 + fq * 8), b = *(const f32x4*)(ssq + (size_t)row * 32 + fq * 8 + 4);
;     float s = ((a[0] + a[1]) + (a[2] + a[3])) + ((b[0] + b[1]) + (b[2] + b[3]));
;     s += __shfl_xor(s, 16); s += __shfl_xor(s, 32);
;     return __builtin_amdgcn_rsqf(s * (1.0f / 2048.0f) + 1e-6f);
; }
;     ...
;         const float rs = pg8::row_rs(ssq, grow0 + 16 * w + fr, fq);
;         float sq = 0.f;
; #pragma unroll
;         for (int nb = 0; nb < 8; ++nb) { acc[nb] = acc[nb] * rs; sq += (acc[nb][0] * acc[nb][0] + acc[nb][1] * acc[nb][1]) + (acc[nb][2] * acc[nb][2] + acc[nb][3] * acc[nb][3]); }
;         sq += __shfl_xor(sq, 16); sq += __shfl_xor(sq, 32);
;         const float rn = __builtin_amdgcn_rsqf(sq * (1.f / 128.f) + EPS) * QSCALE;
; #pragma unroll
;         for (int nb = 0; nb < 8; ++nb) { const f32x4 gv = *(const f32x4*)(qg + 16 * nb + 4 * fq);
;             u32x2 ov; ov.x = pk2(acc[nb][0] * rn * gv[0], acc[nb][1] * rn * gv[1]); ov.y = pk2(acc[nb][2] * rn * gv[2], acc[nb][3] * rn * gv[3]);
;             *(LAS u32x2*)(Qs + (16 * w + fr) * QP + 16 * nb + 4 * fq) = ov; }
.LBB0_57:
	s_waitcnt vmcnt(3)
	v_or_b32_e32 v36, s74, v146
	v_add_u32_e32 v36, v36, v151
	v_ashrrev_i32_e32 v37, 31, v36
	s_waitcnt vmcnt(1)
	v_lshrrev_b32_e32 v78, 4, v161
	v_lshlrev_b64 v[36:37], 7, v[36:37]
	v_lshl_add_u64 v[36:37], s[60:61], 0, v[36:37]
	v_lshlrev_b32_e32 v38, 5, v78
	v_mov_b32_e32 v39, v153
	v_lshl_add_u64 v[40:41], v[36:37], 0, v[38:39]
	global_load_dwordx4 v[36:39], v[40:41], off
	s_nop 0
	global_load_dwordx4 v[40:43], v[40:41], off offset:16
	v_lshlrev_b32_e32 v79, 3, v78
	s_movk_i32 s0, 0x500
	s_mov_b64 s[14:15], 0x40000
	v_bfe_u32 v197, v133, 6, 1
	v_readlane_b32 s16, v255, 15
	v_lshlrev_b32_e32 v156, 2, v78
	v_mov_b32_e32 v236, v181
	v_mov_b32_e32 v237, 0xff800000
	v_mov_b32_e32 v181, 0x3e0293ee
	v_mov_b32_e32 v238, v186
	s_waitcnt vmcnt(1)
	v_mov_b32_e32 v44, v36
	s_waitcnt vmcnt(0)
	v_mov_b32_e32 v45, v40
	v_mov_b32_e32 v40, v37
	v_pk_add_f32 v[36:37], v[44:45], v[40:41]
	v_mov_b32_e32 v40, v38
	v_mov_b32_e32 v41, v42
	v_mov_b32_e32 v42, v39
	v_pk_add_f32 v[38:39], v[40:41], v[42:43]
	s_nop 0
	v_pk_add_f32 v[36:37], v[36:37], v[38:39]
	s_nop 0
	v_add_f32_e32 v36, v36, v37
	ds_bpermute_b32 v37, v193, v36
	s_waitcnt lgkmcnt(0)
	v_add_f32_e32 v36, v36, v37
	ds_bpermute_b32 v37, v194, v36
	s_waitcnt lgkmcnt(0)
	v_add_f32_e32 v36, v36, v37
	v_fmamk_f32 v36, v36, 0x3a000000, v177
	v_rsq_f32_e32 v36, v36
	s_nop 0
	v_pk_mul_f32 v[70:71], v[128:129], v[36:37] op_sel_hi:[1,0]
	v_pk_mul_f32 v[66:67], v[124:125], v[36:37] op_sel_hi:[1,0]
	v_pk_mul_f32 v[68:69], v[130:131], v[36:37] op_sel_hi:[1,0]
	v_pk_mul_f32 v[64:65], v[126:127], v[36:37] op_sel_hi:[1,0]
	v_mov_b32_e32 v40, v71
	v_mov_b32_e32 v41, v67
	v_mov_b32_e32 v38, v70
	v_mov_b32_e32 v39, v66
	v_pk_mul_f32 v[40:41], v[40:41], v[40:41]
	v_mov_b32_e32 v42, v69
	v_mov_b32_e32 v43, v65
	v_pk_fma_f32 v[38:39], v[38:39], v[38:39], v[40:41]
	v_mov_b32_e32 v40, v68
	v_mov_b32_e32 v41, v64
	v_pk_mul_f32 v[42:43], v[42:43], v[42:43]
	v_pk_mul_f32 v[60:61], v[122:123], v[36:37] op_sel_hi:[1,0]
	v_pk_fma_f32 v[40:41], v[40:41], v[40:41], v[42:43]
	v_pk_mul_f32 v[62:63], v[120:121], v[36:37] op_sel_hi:[1,0]
	v_pk_add_f32 v[38:39], v[38:39], v[40:41]
	v_pk_mul_f32 v[40:41], v[60:61], v[60:61]
	v_pk_add_f32 v[38:39], v[38:39], v[38:39] op_sel_hi:[0,1]
	v_pk_mul_f32 v[42:43], v[62:63], v[62:63]
	v_pk_mul_f32 v[58:59], v[116:117], v[36:37] op_sel_hi:[1,0]
	v_pk_mov_b32 v[44:45], v[42:43], v[40:41] op_sel:[1,0]
	v_mov_b32_e32 v43, v41
	v_pk_mul_f32 v[56:57], v[118:119], v[36:37] op_sel_hi:[1,0]
	v_mul_f32_e32 v38, v58, v58
	v_pk_add_f32 v[40:41], v[44:45], v[42:43]
	v_pk_fma_f32 v[42:43], v[58:59], v[58:59], v[38:39] op_sel_hi:[1,1,0]
	v_mul_f32_e32 v38, v56, v56
	v_pk_add_f32 v[40:41], v[40:41], v[40:41] op_sel_hi:[0,1]
	v_pk_fma_f32 v[44:45], v[56:57], v[56:57], v[38:39] op_sel_hi:[1,1,0]
	v_pk_mul_f32 v[52:53], v[114:115], v[36:37] op_sel_hi:[1,0]
	v_pk_mul_f32 v[54:55], v[112:113], v[36:37] op_sel_hi:[1,0]
	v_mul_f32_e32 v40, v52, v52
	v_mul_f32_e32 v42, v54, v54
	v_mul_f32_e32 v44, v55, v55
	v_mul_f32_e32 v38, v53, v53
	v_pk_add_f32 v[42:43], v[42:43], v[44:45]
	v_pk_add_f32 v[38:39], v[40:41], v[38:39]
	v_pk_mul_f32 v[48:49], v[110:111], v[36:37] op_sel_hi:[1,0]
	v_pk_mul_f32 v[50:51], v[108:109], v[36:37] op_sel_hi:[1,0]
	v_pk_add_f32 v[38:39], v[42:43], v[38:39]
	v_pk_mul_f32 v[40:41], v[48:49], v[48:49]
	v_pk_mul_f32 v[42:43], v[50:51], v[50:51]
	v_pk_add_f32 v[38:39], v[38:39], v[38:39] op_sel_hi:[0,1]
	v_pk_mov_b32 v[44:45], v[42:43], v[40:41] op_sel:[1,0]
	v_mov_b32_e32 v43, v41
	v_pk_mul_f32 v[46:47], v[104:105], v[36:37] op_sel_hi:[1,0]
	v_pk_add_f32 v[40:41], v[44:45], v[42:43]
	v_pk_mul_f32 v[44:45], v[106:107], v[36:37] op_sel_hi:[1,0]
	v_mul_f32_e32 v38, v46, v46
	v_pk_fma_f32 v[74:75], v[46:47], v[46:47], v[38:39] op_sel_hi:[1,1,0]
	v_mul_f32_e32 v38, v44, v44
	v_pk_add_f32 v[72:73], v[40:41], v[40:41] op_sel_hi:[0,1]
	v_pk_fma_f32 v[76:77], v[44:45], v[44:45], v[38:39] op_sel_hi:[1,1,0]
	v_pk_mul_f32 v[40:41], v[102:103], v[36:37] op_sel_hi:[1,0]
	v_pk_mul_f32 v[42:43], v[100:101], v[36:37] op_sel_hi:[1,0]
	v_mul_f32_e32 v72, v40, v40
	v_mul_f32_e32 v74, v42, v42
	v_mul_f32_e32 v76, v43, v43
	v_mul_f32_e32 v38, v41, v41
	v_pk_add_f32 v[36:37], v[74:75], v[76:77]
	v_pk_add_f32 v[38:39], v[72:73], v[38:39]
	v_and_b32_e32 v74, 48, v161
	v_pk_add_f32 v[36:37], v[36:37], v[38:39]
	s_nop 0
	v_add_f32_e32 v36, v36, v37
	ds_bpermute_b32 v37, v193, v36
	s_waitcnt lgkmcnt(0)
	v_add_f32_e32 v36, v36, v37
	ds_bpermute_b32 v37, v194, v36
	s_waitcnt lgkmcnt(0)
	v_add_f32_e32 v36, v36, v37
	v_fmamk_f32 v36, v36, 0x3c000000, v177
	v_rsq_f32_e32 v36, v36
	s_nop 0
	v_mul_f32_e32 v72, 0x3e0293ee, v36
	v_mul_lo_u32 v36, v149, s94
	v_add3_u32 v73, 0, v36, v79
	global_load_dwordx4 v[200:203], v74, s[76:77]
	global_load_dwordx4 v[204:207], v74, s[76:77] offset:64
	global_load_dwordx4 v[208:211], v74, s[76:77] offset:128
	global_load_dwordx4 v[212:215], v74, s[76:77] offset:192
	global_load_dwordx4 v[216:219], v74, s[76:77] offset:256
	global_load_dwordx4 v[220:223], v74, s[76:77] offset:320
	global_load_dwordx4 v[224:227], v74, s[76:77] offset:384
	global_load_dwordx4 v[228:231], v74, s[76:77] offset:448
	v_mul_f32_e32 v70, v70, v72
	v_mul_f32_e32 v66, v66, v72
	v_mul_f32_e32 v62, v62, v72
	v_mul_f32_e32 v58, v58, v72
	v_mul_f32_e32 v54, v54, v72
	v_mul_f32_e32 v50, v50, v72
	v_mul_f32_e32 v46, v46, v72
	v_mul_f32_e32 v42, v42, v72
	s_waitcnt vmcnt(7)
	v_mul_f32_e32 v36, v200, v70
	v_mul_f32_e32 v70, v71, v72
	v_mul_f32_e32 v37, v201, v70
	v_cvt_pk_bf16_f32 v36, v36, v37
	v_mul_f32_e32 v37, v68, v72
	v_mul_f32_e32 v37, v202, v37
	v_mul_f32_e32 v38, v69, v72
	v_mul_f32_e32 v38, v203, v38
	v_cvt_pk_bf16_f32 v37, v37, v38
	ds_write_b64 v73, v[36:37]
	s_waitcnt vmcnt(6)
; #define LAS __attribute__((address_space(3)))
; __device__ __forceinline__ float bflo(unsigned w) { return __uint_as_float(w << 16); }
; __device__ __forceinline__ float bfhi(unsigned w) { return __uint_as_float(w & 0xffff0000u); }
; __device__ __forceinline__ unsigned pk2(float lo, float hi) { return pg8::cvt_pk_bf16(lo, hi); }
;     ...
;     auto norm16 = [&](u32x4& a, u32x4& b, const float* gn, float extra) {
;         float x[16];
; #pragma unroll
;         for (int e = 0; e < 4; ++e) { x[2 * e] = bflo(a[e]); x[2 * e + 1] = bfhi(a[e]); x[8 + 2 * e] = bflo(b[e]); x[9 + 2 * e] = bfhi(b[e]); }
;         float sq = 0.f;
; #pragma unroll
;         for (int e = 0; e < 16; ++e) sq += x[e] * x[e];
;         sq += __shfl_xor(sq, 1); sq += __shfl_xor(sq, 2); sq += __shfl_xor(sq, 4);
;         const float rs = __builtin_amdgcn_rsqf(sq * (1.f / 128.f) + EPS) * extra;
;     ...
;         for (int nb = 0; nb < 8; ++nb) { const f32x4 gv = *(const f32x4*)(qg + 16 * nb + 4 * fq);
;             u32x2 ov; ov.x = pk2(acc[nb][0] * rn * gv[0], acc[nb][1] * rn * gv[1]); ov.y = pk2(acc[nb][2] * rn * gv[2], acc[nb][3] * rn * gv[3]);
;             *(LAS u32x2*)(Qs + (16 * w + fr) * QP + 16 * nb + 4 * fq) = ov; }
;         __syncthreads();
	v_mul_f32_e32 v36, v204, v66
	v_mul_f32_e32 v66, v67, v72
	v_mul_f32_e32 v37, v205, v66
	v_cvt_pk_bf16_f32 v36, v36, v37
	v_mul_f32_e32 v37, v64, v72
	v_mul_f32_e32 v37, v206, v37
	v_mul_f32_e32 v38, v65, v72
	v_mul_f32_e32 v38, v207, v38
	v_cvt_pk_bf16_f32 v37, v37, v38
	ds_write_b64 v73, v[36:37] offset:32
	v_mul_lo_u32 v64, v148, s0
	v_readlane_b32 s0, v255, 14
	s_waitcnt vmcnt(5)
	v_mul_f32_e32 v36, v208, v62
	v_mul_f32_e32 v62, v63, v72
	v_mul_f32_e32 v37, v209, v62
	v_cvt_pk_bf16_f32 v36, v36, v37
	v_mul_f32_e32 v37, v60, v72
	v_mul_f32_e32 v37, v210, v37
	v_mul_f32_e32 v38, v61, v72
	v_mul_f32_e32 v38, v211, v38
	v_cvt_pk_bf16_f32 v37, v37, v38
	ds_write_b64 v73, v[36:37] offset:64
	s_waitcnt vmcnt(4)
	v_mul_f32_e32 v36, v212, v58
	v_mul_f32_e32 v58, v59, v72
	v_mul_f32_e32 v37, v213, v58
	v_cvt_pk_bf16_f32 v36, v36, v37
	v_mul_f32_e32 v37, v56, v72
	v_mul_f32_e32 v37, v214, v37
	v_mul_f32_e32 v38, v57, v72
	v_mul_f32_e32 v38, v215, v38
	v_cvt_pk_bf16_f32 v37, v37, v38
	ds_write_b64 v73, v[36:37] offset:96
	v_lshlrev_b32_e32 v56, 16, v30
	v_and_b32_e32 v57, 0xffff0000, v30
	v_lshlrev_b32_e32 v58, 16, v35
	v_and_b32_e32 v59, 0xffff0000, v35
	s_waitcnt vmcnt(3)
	v_mul_f32_e32 v36, v216, v54
	v_mul_f32_e32 v54, v55, v72
	v_mul_f32_e32 v37, v217, v54
	v_cvt_pk_bf16_f32 v36, v36, v37
	v_mul_f32_e32 v37, v52, v72
	v_mul_f32_e32 v37, v218, v37
	v_mul_f32_e32 v38, v53, v72
	v_mul_f32_e32 v38, v219, v38
	v_cvt_pk_bf16_f32 v37, v37, v38
	ds_write_b64 v73, v[36:37] offset:128
	v_lshlrev_b32_e32 v54, 16, v34
	v_and_b32_e32 v55, 0xffff0000, v34
	v_lshlrev_b32_e32 v52, 16, v29
	v_and_b32_e32 v53, 0xffff0000, v29
	s_waitcnt vmcnt(2)
	v_mul_f32_e32 v36, v220, v50
	v_mul_f32_e32 v50, v51, v72
	v_mul_f32_e32 v37, v221, v50
	v_cvt_pk_bf16_f32 v36, v36, v37
	v_mul_f32_e32 v37, v48, v72
	v_mul_f32_e32 v37, v222, v37
	v_mul_f32_e32 v38, v49, v72
	v_mul_f32_e32 v38, v223, v38
	v_cvt_pk_bf16_f32 v37, v37, v38
	ds_write_b64 v73, v[36:37] offset:160
	v_lshlrev_b32_e32 v50, 16, v33
	v_and_b32_e32 v51, 0xffff0000, v33
	v_lshlrev_b32_e32 v48, 16, v28
	v_and_b32_e32 v49, 0xffff0000, v28
	s_waitcnt vmcnt(1)
	v_mul_f32_e32 v36, v224, v46
	v_mul_f32_e32 v46, v47, v72
	v_mul_f32_e32 v37, v225, v46
	v_cvt_pk_bf16_f32 v36, v36, v37
	v_mul_f32_e32 v37, v44, v72
	v_mul_f32_e32 v37, v226, v37
	v_mul_f32_e32 v38, v45, v72
	v_mul_f32_e32 v38, v227, v38
	v_cvt_pk_bf16_f32 v37, v37, v38
	ds_write_b64 v73, v[36:37] offset:192
	v_and_b32_e32 v47, 0xffff0000, v32
	v_lshlrev_b32_e32 v46, 16, v32
	v_mul_f32_e32 v30, v47, v47
	v_fmac_f32_e32 v30, v46, v46
	v_fmac_f32_e32 v30, v50, v50
	v_fmac_f32_e32 v30, v51, v51
	v_fmac_f32_e32 v30, v54, v54
	v_fmac_f32_e32 v30, v55, v55
	v_fmac_f32_e32 v30, v58, v58
	v_fmac_f32_e32 v30, v59, v59
	v_fmac_f32_e32 v30, v48, v48
	v_fmac_f32_e32 v30, v49, v49
	v_fmac_f32_e32 v30, v52, v52
	v_fmac_f32_e32 v30, v53, v53
	v_fmac_f32_e32 v30, v56, v56
	v_and_b32_e32 v44, 0xffff0000, v31
	v_lshlrev_b32_e32 v45, 16, v31
	v_fmac_f32_e32 v30, v57, v57
	v_pk_mul_f32 v[28:29], v[44:45], v[44:45]
	s_waitcnt vmcnt(0)
	v_mul_f32_e32 v36, v42, v228
	v_add_f32_e32 v29, v29, v30
	v_add_f32_e32 v28, v28, v29
	ds_bpermute_b32 v29, v155, v28
	v_mul_f32_e32 v42, v43, v72
	v_mul_f32_e32 v37, v42, v229
	v_cvt_pk_bf16_f32 v36, v36, v37
	v_mul_f32_e32 v37, v40, v72
	s_waitcnt lgkmcnt(0)
	v_add_f32_e32 v28, v28, v29
	ds_bpermute_b32 v29, v157, v28
	v_mul_f32_e32 v37, v37, v230
	v_mul_f32_e32 v38, v41, v72
	v_mul_f32_e32 v38, v38, v231
	v_cvt_pk_bf16_f32 v37, v37, v38
	s_waitcnt lgkmcnt(0)
	v_add_f32_e32 v28, v28, v29
	ds_bpermute_b32 v29, v192, v28
	v_lshlrev_b32_e32 v40, 2, v140
	v_mov_b32_e32 v41, v153
	ds_write_b64 v73, v[36:37] offset:224
	s_waitcnt lgkmcnt(0)
	v_add_f32_e32 v28, v28, v29
	v_fmamk_f32 v28, v28, 0x3c000000, v177
	s_barrier
;     ...
;         const float rs = __builtin_amdgcn_rsqf(sq * (1.f / 128.f) + EPS) * extra;
;         const f32x4 g0 = *(const f32x4*)(gn + 8 * kj), g1 = *(const f32x4*)(gn + 8 * kj + 4), g2 = *(const f32x4*)(gn + 64 + 8 * kj), g3 = *(const f32x4*)(gn + 64 + 8 * kj + 4);
;         a[0] = pk2(x[0] * rs * g0[0], x[1] * rs * g0[1]); a[1] = pk2(x[2] * rs * g0[2], x[3] * rs * g0[3]); a[2] = pk2(x[4] * rs * g1[0], x[5] * rs * g1[1]); a[3] = pk2(x[6] * rs * g1[2], x[7] * rs * g1[3]);
;         b[0] = pk2(x[8] * rs * g2[0], x[9] * rs * g2[1]); b[1] = pk2(x[10] * rs * g2[2], x[11] * rs * g2[3]); b[2] = pk2(x[12] * rs * g3[0], x[13] * rs * g3[1]); b[3] = pk2(x[14] * rs * g3[2], x[15] * rs * g3[3]);
;     };
;     auto load_tile = [&](KVRegs& r, int t) {
;         const bf16* ks = Kp + (size_t)(t * 64 + kr) * ldkv; r.ka = *(const u32x4*)(ks + 8 * kj); r.kb = *(const u32x4*)(ks + 64 + 8 * kj);
;         if (MODE == 0) { const bf16* vs = Vp + (size_t)(tid >> 2) * SEQ + t * 64 + 16 * (tid & 3); r.va = *(const u32x4*)vs; r.vb = *(const u32x4*)(vs + 8); }
;         else { const bf16* vs = Vp + (size_t)(t * 64 + vr) * ldkv; r.va = *(const u32x4*)(vs + 8 * vj); r.vb = *(const u32x4*)(vs + 64 + 8 * vj); } };
;     auto stage = [&](KVRegs& r, int buf) {
;         LAS bf16* Ks = (LAS bf16*)(lds + koff(buf)); LAS bf16* VT = (LAS bf16*)(lds + voff(buf));
;         if (MODE >= 1) norm16(r.ka, r.kb, kg, 1.0f);
;         *(LAS u32x4*)(Ks + kr * QP + 8 * kj) = r.ka; *(LAS u32x4*)(Ks + kr * QP + 64 + 8 * kj) = r.kb;
;         if (MODE == 0) { *(LAS u32x4*)(VT + (tid >> 2) * VPA + 16 * (tid & 3)) = r.va; *(LAS u32x4*)(VT + (tid >> 2) * VPA + 16 * (tid & 3) + 8) = r.vb; }
;         else
; #pragma unroll
;         for (int e = 0; e < 4; ++e) { const int pv = vperm(vr);
;                                       VT[(8 * vj + 2 * e) * VPA + pv] = (bf16)(r.va[e] & 0xffffu); VT[(8 * vj + 2 * e + 1) * VPA + pv] = (bf16)(r.va[e] >> 16);
;                                       VT[(64 + 8 * vj + 2 * e) * VPA + pv] = (bf16)(r.vb[e] & 0xffffu); VT[(64 + 8 * vj + 2 * e + 1) * VPA + pv] = (bf16)(r.vb[e] >> 16); } };
;     ...
;     stage(r0, 0); if (2 < ntiles) load_tile(r0, 2);
;     if (MODE == 0) { stage(r1, 1); if (3 < ntiles) load_tile(r1, 3); }
;     __syncthreads();
;     const int rp = w >> 1, kh = w & 1;
;     bf16x8 qf[2][4];
; #pragma unroll
;     for (int rb = 0; rb < 2; ++rb)
; #pragma unroll
	v_rsq_f32_e32 v60, v28
	v_lshl_add_u64 v[158:159], s[40:41], 0, v[40:41]
	global_load_dwordx4 v[28:31], v40, s[40:41] offset:16
	global_load_dwordx4 v[32:35], v40, s[40:41]
	global_load_dwordx4 v[36:39], v40, s[40:41] offset:272
	s_nop 0
	global_load_dwordx4 v[40:43], v40, s[40:41] offset:256
	s_mov_b64 s[40:41], -1
	v_mul_f32_e32 v46, v60, v46
	s_waitcnt vmcnt(2)
	v_mul_f32_e32 v32, v32, v46
	v_mul_f32_e32 v46, v60, v47
	v_mul_f32_e32 v33, v33, v46
	v_cvt_pk_bf16_f32 v32, v32, v33
	v_mul_f32_e32 v33, v60, v50
	v_mul_f32_e32 v33, v34, v33
	v_mul_f32_e32 v34, v60, v51
	v_mul_f32_e32 v34, v35, v34
	v_cvt_pk_bf16_f32 v33, v33, v34
	v_mul_f32_e32 v34, v60, v54
	v_mul_f32_e32 v28, v28, v34
	v_mul_f32_e32 v34, v60, v55
	v_mul_f32_e32 v29, v29, v34
	v_cvt_pk_bf16_f32 v34, v28, v29
	v_mul_f32_e32 v28, v60, v58
	v_mul_f32_e32 v29, v60, v59
	v_mul_f32_e32 v28, v30, v28
	v_mul_f32_e32 v29, v31, v29
	v_cvt_pk_bf16_f32 v35, v28, v29
	v_mul_f32_e32 v28, v60, v48
	v_mul_f32_e32 v29, v60, v49
	s_waitcnt vmcnt(0)
	v_mul_f32_e32 v28, v40, v28
	v_mul_f32_e32 v29, v41, v29
	v_cvt_pk_bf16_f32 v28, v28, v29
	v_mul_f32_e32 v29, v60, v52
	v_mul_f32_e32 v30, v60, v53
	v_mul_f32_e32 v29, v42, v29
	v_mul_f32_e32 v30, v43, v30
	v_cvt_pk_bf16_f32 v29, v29, v30
	v_mul_f32_e32 v30, v60, v56
	v_mul_f32_e32 v31, v60, v57
	v_mul_f32_e32 v30, v36, v30
	v_mul_f32_e32 v31, v37, v31
	v_cvt_pk_bf16_f32 v30, v30, v31
	v_mul_f32_e32 v31, v60, v45
	v_mul_f32_e32 v36, v60, v44
	v_mul_f32_e32 v31, v38, v31
	v_mul_f32_e32 v36, v39, v36
	v_cvt_pk_bf16_f32 v31, v31, v36
	v_mul_lo_u32 v36, v138, s94
	v_add_u32_e32 v36, 0, v36
	v_add_u32_e32 v195, v36, v152
	ds_write_b128 v195, v[32:35] offset:36864
	ds_write_b128 v195, v[28:31] offset:36992
	v_lshlrev_b32_e32 v28, 1, v161
	v_lshrrev_b32_e32 v29, 2, v133
	v_and_b32_e32 v28, 24, v28
	v_and_b32_e32 v29, 4, v29
	v_and_b32_e32 v30, 35, v133
	v_or3_b32 v28, v29, v30, v28
	v_lshlrev_b32_e32 v65, 1, v28
	v_add3_u32 v196, s0, v64, v65
	ds_write_b16 v196, v24
	ds_write_b16_d16_hi v196, v24 offset:160
	ds_write_b16 v196, v20 offset:10240
	ds_write_b16_d16_hi v196, v20 offset:10400
	ds_write_b16 v196, v25 offset:320
	ds_write_b16_d16_hi v196, v25 offset:480
	ds_write_b16 v196, v21 offset:10560
	ds_write_b16_d16_hi v196, v21 offset:10720
	ds_write_b16 v196, v26 offset:640
	ds_write_b16_d16_hi v196, v26 offset:800
	ds_write_b16 v196, v22 offset:10880
	ds_write_b16_d16_hi v196, v22 offset:11040
	ds_write_b16 v196, v27 offset:960
	ds_write_b16_d16_hi v196, v27 offset:1120
	ds_write_b16 v196, v23 offset:11200
	ds_write_b16_d16_hi v196, v23 offset:11360
	v_lshlrev_b64 v[20:21], 11, v[138:139]
	v_lshlrev_b32_e32 v152, 1, v140
	v_lshl_add_u64 v[20:21], s[36:37], 0, v[20:21]
	v_lshl_add_u64 v[20:21], v[20:21], 0, v[152:153]
	v_lshl_add_u64 v[22:23], v[20:21], 0, s[14:15]
	s_mov_b32 s14, 0x40000
	v_add_co_u32_e32 v24, vcc, s14, v20
	v_ashrrev_i32_e32 v152, 7, v133
	s_nop 0
	v_addc_co_u32_e32 v25, vcc, 0, v21, vcc
	global_load_dwordx4 v[80:83], v[24:25], off
	global_load_dwordx4 v[88:91], v[22:23], off offset:128
	v_lshl_add_u64 v[22:23], v[136:137], 1, v[134:135]
	v_add_co_u32_e32 v28, vcc, s14, v22
	v_lshl_or_b32 v160, v152, 5, v146
	s_nop 0
	v_addc_co_u32_e32 v29, vcc, 0, v23, vcc
	global_load_dwordx4 v[24:27], v[28:29], off
	s_nop 0
	global_load_dwordx4 v[28:31], v[28:29], off offset:128
	v_mad_u64_u32 v[60:61], s[14:15], v160, s94, v[132:133]
	s_waitcnt lgkmcnt(0)
	s_barrier
	ds_read_b128 v[32:35], v60
	ds_read_b128 v[36:39], v60 offset:64
	ds_read_b128 v[40:43], v60 offset:128
	ds_read_b128 v[44:47], v60 offset:192
	ds_read_b128 v[48:51], v60 offset:4608
	ds_read_b128 v[52:55], v60 offset:4672
	ds_read_b128 v[56:59], v60 offset:4736
	ds_read_b128 v[60:63], v60 offset:4800
	s_mov_b64 s[14:15], 0x60000
	v_lshl_add_u64 v[162:163], v[20:21], 0, s[14:15]
	v_lshl_or_b32 v20, v197, 5, v146
	v_lshl_add_u64 v[164:165], v[22:23], 0, s[14:15]
	s_mov_b64 s[14:15], 0x60080
	v_mul_u32_u24_e32 v21, 0x120, v20
	v_lshlrev_b32_e32 v20, 6, v197
	v_lshl_add_u64 v[166:167], v[22:23], 0, s[14:15]
	v_add3_u32 v22, s0, v20, v147
	v_add3_u32 v23, s16, v20, v147
	v_mov_b32_e32 v20, 0
	v_add3_u32 v198, s16, v64, v65
	v_add_u32_e32 v207, v22, v141
	v_add_u32_e32 v208, v23, v141
	v_add_u32_e32 v209, v132, v21
	v_mov_b32_e32 v21, v20
	v_mov_b32_e32 v22, v20
	v_mov_b32_e32 v23, v20
	v_mov_b32_e32 v64, v20
	v_mov_b32_e32 v65, v20
	v_mov_b32_e32 v66, v20
	v_mov_b32_e32 v67, v20
	v_mov_b32_e32 v68, v20
	v_mov_b32_e32 v69, v20
	v_mov_b32_e32 v70, v20
	v_mov_b32_e32 v71, v20
	v_mov_b32_e32 v72, v20
	v_mov_b32_e32 v73, v20
	v_mov_b32_e32 v74, v20
	v_mov_b32_e32 v75, v20
	v_mov_b32_e32 v76, v20
	v_mov_b32_e32 v77, v20
	v_mov_b32_e32 v78, v20
	v_mov_b32_e32 v79, v20
	v_mov_b32_e32 v84, v20
	v_mov_b32_e32 v85, v20
	v_mov_b32_e32 v86, v20
	v_mov_b32_e32 v87, v20
	v_mov_b32_e32 v92, v20
	v_mov_b32_e32 v93, v20
	v_mov_b32_e32 v94, v20
	v_mov_b32_e32 v95, v20
	v_mov_b32_e32 v96, v20
	v_mov_b32_e32 v97, v20
	v_mov_b32_e32 v98, v20
	v_mov_b32_e32 v99, v20
	v_mov_b32_e32 v100, v20
	v_mov_b32_e32 v101, v20
	v_mov_b32_e32 v102, v20
	v_mov_b32_e32 v103, v20
	v_mov_b32_e32 v104, v20
	v_mov_b32_e32 v105, v20
	v_mov_b32_e32 v106, v20
	v_mov_b32_e32 v107, v20
	v_mov_b32_e32 v108, v20
	v_mov_b32_e32 v109, v20
	v_mov_b32_e32 v110, v20
	v_mov_b32_e32 v111, v20
	v_mov_b32_e32 v112, v20
	v_mov_b32_e32 v113, v20
	v_mov_b32_e32 v114, v20
	v_mov_b32_e32 v115, v20
	v_mov_b32_e32 v116, v20
	v_mov_b32_e32 v117, v20
	v_mov_b32_e32 v118, v20
	v_mov_b32_e32 v119, v20
	v_mov_b32_e32 v120, v20
	v_mov_b32_e32 v121, v20
	v_mov_b32_e32 v122, v20
	v_mov_b32_e32 v123, v20
	v_mov_b32_e32 v124, v20
	v_mov_b32_e32 v125, v20
	s_waitcnt vmcnt(1)
	v_lshrrev_b32_e32 v199, 16, v24
	s_waitcnt vmcnt(0)
	v_lshrrev_b32_e32 v200, 16, v28
	v_lshrrev_b32_e32 v201, 16, v25
	v_lshrrev_b32_e32 v202, 16, v29
	v_lshrrev_b32_e32 v203, 16, v26
	v_lshrrev_b32_e32 v204, 16, v30
	v_lshrrev_b32_e32 v205, 16, v27
	v_lshrrev_b32_e32 v206, 16, v31
	v_mov_b32_e32 v126, v20
	v_mov_b32_e32 v127, v20
	v_mov_b32_e32 v128, v20
	v_mov_b32_e32 v129, v20
	v_mov_b32_e32 v130, v20
	v_mov_b32_e32 v131, v20
	v_mov_b32_e32 v168, v20
	v_mov_b32_e32 v169, v20
	s_branch .LBB0_59

; #define LAS __attribute__((address_space(3)))
; #define MMA16(X, Y, ACC) ACC = __builtin_amdgcn_mfma_f32_16x16x32_bf16((X), (Y), (ACC), 0, 0, 0)
; __global__ void __launch_bounds__(512, 2) fwd_mega(Args args) {
;     ...
;                 for (int rb = bx; rb < TOK / 32; rb += G) {
;                     f32x4 a2[2] = {(f32x4){0.f, 0.f, 0.f, 0.f}, (f32x4){0.f, 0.f, 0.f, 0.f}};
; #pragma unroll
;                     for (int ks = 0; ks < 8; ++ks) { const int k = wave * 256 + 32 * ks + 8 * fq;
;                         const bf16x8 wf = *(const bf16x8*)(Win + (size_t)(PROJW + fr) * DM + k);
; #pragma unroll
;                         for (int r2 = 0; r2 < 2; ++r2) { const bf16x8 hf = *(const bf16x8*)(Hb + (size_t)(rb * 32 + 16 * r2 + fr) * DM + k); MMA16(wf, hf, a2[r2]); } }
; #pragma unroll
;                     for (int r2 = 0; r2 < 2; ++r2) *(LAS f32x4*)(red + (wave * 32 + 16 * r2 + fr) * 16 + 4 * fq) = a2[r2];
;                     __syncthreads();
;                     { const int r = tid >> 4, c = tid & 15; float s = 0.f;
; #pragma unroll
;                       for (int ww = 0; ww < 8; ++ww) s += red[(ww * 32 + r) * 16 + c];
;                       const int row = rb * 32 + r; float q = 0.f;
; #pragma unroll
;                       for (int e = 0; e < 32; ++e) q += SSQ[(size_t)row * 32 + e];
;                       GLR[(size_t)row * 16 + c] = s * __builtin_amdgcn_rsqf(q * (1.f / 2048.f) + EPS); }
;                     __syncthreads();
;                 }
.LBB0_190:
	s_nop 0
	v_add_u32_e32 v46, s0, v38
	v_ashrrev_i32_e32 v47, 31, v46
	v_lshlrev_b64 v[54:55], 12, v[46:47]
	v_add_u32_e32 v46, 16, v46
	v_ashrrev_i32_e32 v47, 31, v46
	v_lshlrev_b64 v[58:59], 12, v[46:47]
	v_add_u32_e32 v62, s0, v39
	v_ashrrev_i32_e32 v63, 31, v62
	global_load_dwordx4 v[66:69], v[2:3], off
	v_lshl_add_u64 v[42:43], v[4:5], 0, v[54:55]
	v_lshl_add_u64 v[46:47], v[4:5], 0, v[58:59]
	global_load_dwordx4 v[98:101], v[42:43], off
	global_load_dwordx4 v[188:191], v[46:47], off
	v_lshl_add_u64 v[36:37], s[12:13], 0, v[54:55]
	v_lshl_add_u64 v[34:35], s[12:13], 0, v[58:59]
	global_load_dwordx4 v[70:73], v[6:7], off
	v_lshl_add_u64 v[42:43], v[36:37], 0, v[20:21]
	v_lshl_add_u64 v[46:47], v[34:35], 0, v[20:21]
	global_load_dwordx4 v[102:105], v[42:43], off
	global_load_dwordx4 v[192:195], v[46:47], off
	global_load_dwordx4 v[74:77], v[8:9], off
	v_lshl_add_u64 v[42:43], v[36:37], 0, v[22:23]
	v_lshl_add_u64 v[46:47], v[34:35], 0, v[22:23]
	global_load_dwordx4 v[106:109], v[42:43], off
	global_load_dwordx4 v[196:199], v[46:47], off
	global_load_dwordx4 v[78:81], v[10:11], off
	v_lshl_add_u64 v[42:43], v[36:37], 0, v[24:25]
	v_lshl_add_u64 v[46:47], v[34:35], 0, v[24:25]
	global_load_dwordx4 v[110:113], v[42:43], off
	global_load_dwordx4 v[200:203], v[46:47], off
	global_load_dwordx4 v[82:85], v[12:13], off
	v_lshl_add_u64 v[42:43], v[36:37], 0, v[26:27]
	v_lshl_add_u64 v[46:47], v[34:35], 0, v[26:27]
	global_load_dwordx4 v[114:117], v[42:43], off
	global_load_dwordx4 v[204:207], v[46:47], off
	global_load_dwordx4 v[86:89], v[14:15], off
	v_lshl_add_u64 v[42:43], v[36:37], 0, v[28:29]
	v_lshl_add_u64 v[46:47], v[34:35], 0, v[28:29]
	global_load_dwordx4 v[118:121], v[42:43], off
	global_load_dwordx4 v[208:211], v[46:47], off
	global_load_dwordx4 v[90:93], v[16:17], off
	v_lshl_add_u64 v[42:43], v[36:37], 0, v[30:31]
	v_lshl_add_u64 v[46:47], v[34:35], 0, v[30:31]
	global_load_dwordx4 v[122:125], v[42:43], off
	global_load_dwordx4 v[212:215], v[46:47], off
	global_load_dwordx4 v[94:97], v[18:19], off
	v_lshl_add_u64 v[42:43], v[36:37], 0, v[32:33]
	v_lshl_add_u64 v[46:47], v[34:35], 0, v[32:33]
	global_load_dwordx4 v[126:129], v[42:43], off
	global_load_dwordx4 v[216:219], v[46:47], off
	v_lshlrev_b64 v[34:35], 7, v[62:63]
	v_lshl_add_u64 v[64:65], s[60:61], 0, v[34:35]
	global_load_dwordx4 v[220:223], v[64:65], off
	global_load_dwordx4 v[224:227], v[64:65], off offset:16
	global_load_dwordx4 v[228:231], v[64:65], off offset:32
	global_load_dwordx4 v[232:235], v[64:65], off offset:48
	global_load_dwordx4 v[156:159], v[64:65], off offset:64
	global_load_dwordx4 v[160:163], v[64:65], off offset:80
	global_load_dwordx4 v[164:167], v[64:65], off offset:96
	global_load_dwordx4 v[168:171], v[64:65], off offset:112
	s_add_i32 s10, s10, s52
	s_add_i32 s0, s0, s35
	s_cmpk_gt_i32 s10, 0xff
	s_waitcnt vmcnt(30)
	v_mfma_f32_16x16x32_bf16 v[42:45], v[66:69], v[98:101], 0
	s_waitcnt vmcnt(29)
	v_mfma_f32_16x16x32_bf16 v[46:49], v[66:69], v[188:191], 0
	s_waitcnt vmcnt(27)
	v_mfma_f32_16x16x32_bf16 v[42:45], v[70:73], v[102:105], v[42:45]
	s_waitcnt vmcnt(26)
	v_mfma_f32_16x16x32_bf16 v[46:49], v[70:73], v[192:195], v[46:49]
	s_waitcnt vmcnt(24)
	v_mfma_f32_16x16x32_bf16 v[42:45], v[74:77], v[106:109], v[42:45]
	s_waitcnt vmcnt(23)
	v_mfma_f32_16x16x32_bf16 v[46:49], v[74:77], v[196:199], v[46:49]
	s_waitcnt vmcnt(21)
	v_mfma_f32_16x16x32_bf16 v[42:45], v[78:81], v[110:113], v[42:45]
	s_waitcnt vmcnt(20)
	v_mfma_f32_16x16x32_bf16 v[46:49], v[78:81], v[200:203], v[46:49]
	s_waitcnt vmcnt(18)
	v_mfma_f32_16x16x32_bf16 v[42:45], v[82:85], v[114:117], v[42:45]
	s_waitcnt vmcnt(17)
	v_mfma_f32_16x16x32_bf16 v[46:49], v[82:85], v[204:207], v[46:49]
	s_waitcnt vmcnt(15)
	v_mfma_f32_16x16x32_bf16 v[42:45], v[86:89], v[118:121], v[42:45]
	s_waitcnt vmcnt(14)
	v_mfma_f32_16x16x32_bf16 v[46:49], v[86:89], v[208:211], v[46:49]
	s_waitcnt vmcnt(12)
	v_mfma_f32_16x16x32_bf16 v[42:45], v[90:93], v[122:125], v[42:45]
	s_waitcnt vmcnt(11)
	v_mfma_f32_16x16x32_bf16 v[46:49], v[90:93], v[212:215], v[46:49]
	s_waitcnt vmcnt(9)
	v_mfma_f32_16x16x32_bf16 v[42:45], v[94:97], v[126:129], v[42:45]
	s_waitcnt vmcnt(8)
	v_mfma_f32_16x16x32_bf16 v[34:37], v[94:97], v[216:219], v[46:49]
	s_nop 5
	ds_write_b128 v41, v[42:45]
	s_nop 0
	ds_write_b128 v41, v[34:37] offset:1024
	s_waitcnt lgkmcnt(0)
	s_barrier
	ds_read2st64_b32 v[54:55], v40 offset1:8
	ds_read2st64_b32 v[56:57], v40 offset0:16 offset1:24
	ds_read2st64_b32 v[58:59], v40 offset0:32 offset1:40
	ds_read2st64_b32 v[60:61], v40 offset0:48 offset1:56
	s_waitcnt vmcnt(0)
	v_add_f32_e32 v172, 0, v220
	v_add_f32_e32 v172, v172, v221
	v_add_f32_e32 v172, v172, v222
	v_add_f32_e32 v172, v172, v223
	v_add_f32_e32 v172, v172, v224
	v_add_f32_e32 v172, v172, v225
	v_add_f32_e32 v172, v172, v226
	v_add_f32_e32 v172, v172, v227
	v_add_f32_e32 v172, v172, v228
	v_add_f32_e32 v172, v172, v229
	v_add_f32_e32 v172, v172, v230
	v_add_f32_e32 v172, v172, v231
	v_add_f32_e32 v172, v172, v232
	v_add_f32_e32 v172, v172, v233
	v_add_f32_e32 v172, v172, v234
	v_add_f32_e32 v172, v172, v235
	v_add_f32_e32 v172, v172, v156
	v_add_f32_e32 v172, v172, v157
	v_add_f32_e32 v172, v172, v158
	v_add_f32_e32 v172, v172, v159
	v_add_f32_e32 v172, v172, v160
	v_add_f32_e32 v172, v172, v161
	v_add_f32_e32 v172, v172, v162
	v_add_f32_e32 v172, v172, v163
	v_add_f32_e32 v172, v172, v164
	v_add_f32_e32 v172, v172, v165
	v_add_f32_e32 v172, v172, v166
	v_add_f32_e32 v172, v172, v167
	v_add_f32_e32 v172, v172, v168
	v_add_f32_e32 v172, v172, v169
	v_add_f32_e32 v172, v172, v170
	v_add_f32_e32 v172, v172, v171
	s_waitcnt lgkmcnt(3)
	v_add_f32_e32 v173, 0, v54
	v_add_f32_e32 v173, v173, v55
	s_waitcnt lgkmcnt(2)
	v_add_f32_e32 v173, v173, v56
	v_add_f32_e32 v173, v173, v57
	v_fmamk_f32 v34, v172, 0x3a000000, v177
	s_waitcnt lgkmcnt(1)
	v_add_f32_e32 v173, v173, v58
	v_rsq_f32_e32 v34, v34
	v_add_f32_e32 v173, v173, v59
	s_waitcnt lgkmcnt(0)
	v_add_f32_e32 v173, v173, v60
	v_add_f32_e32 v173, v173, v61
	v_mul_f32_e32 v36, v173, v34
	v_lshlrev_b64 v[34:35], 6, v[62:63]
	v_lshl_add_u64 v[34:35], v[0:1], 0, v[34:35]
	global_store_dword v[34:35], v36, off
	s_barrier
	s_cbranch_scc0 .LBB0_190
